# prologue pool-map fold: two dd-batches (26 loads) in flight per iteration instead of one (halves the serial load round trips); on top of normalise hoist
# speedup vs baseline: 1.0086x; 1.0086x over previous
; __device__ __forceinline__ void prologue(const Args& a, LAS unsigned char* lds, int vcu, int G) {
;     ...
;     for (int it = gw; it < DEPTH * 4 * 8 * 16; it += NGW) {
;         const int l = it >> 9, g = (it >> 7) & 3, c8 = (it >> 4) & 7, n = (it & 15) * 64 + lane;
;         const float* wo = a.wout + (size_t)l * DM * DM + (size_t)(g * 64) * DM + n;
;         const float* sc = a.ps + (size_t)l * PWD + g * 64;
;         const float* pr = a.pw + (((size_t)l * 4 + g) * 64 + c8 * 8) * 64;
;         float acc[8] = {0.f, 0.f, 0.f, 0.f, 0.f, 0.f, 0.f, 0.f};
; #pragma unroll 4
;         for (int dd = 0; dd < 64; ++dd) { const float wv = wo[(size_t)dd * DM] * sc[dd];
; #pragma unroll
;             for (int e = 0; e < 8; ++e) acc[e] += pr[e * 64 + dd] * wv; }
.LBB0_87:
	s_add_u32 s30, s27, s18
	v_add_co_u32_e64 v18, s[0:1], s23, v2
	s_addc_u32 s31, s28, s19
	s_nop 0
	v_addc_co_u32_e64 v19, s[0:1], -1, v3, s[0:1]
	v_add_co_u32_e32 v16, vcc, 0xffffd000, v2
	s_add_u32 s0, s14, s18
	s_nop 0
	v_addc_co_u32_e32 v17, vcc, -1, v3, vcc
	s_addc_u32 s1, s17, s19
	global_load_dword v48, v[2:3], off offset:-4096
	global_load_dwordx4 v[12:15], v1, s[30:31]
	global_load_dword v0, v[16:17], off
	global_load_dword v49, v[18:19], off
	s_nop 0
	global_load_dwordx4 v[16:19], v1, s[0:1]
	global_load_dwordx4 v[20:23], v1, s[0:1] offset:256
	global_load_dwordx4 v[24:27], v1, s[0:1] offset:512
	global_load_dwordx4 v[28:31], v1, s[0:1] offset:768
	global_load_dwordx4 v[32:35], v1, s[0:1] offset:1024
	global_load_dwordx4 v[36:39], v1, s[0:1] offset:1280
	global_load_dwordx4 v[40:43], v1, s[0:1] offset:1536
	global_load_dwordx4 v[44:47], v1, s[0:1] offset:1792
	global_load_dword v50, v[2:3], off
	s_add_u32 s18, s18, 16
	s_addc_u32 s19, s19, 0
	v_lshl_add_u64 v[2:3], v[2:3], 0, s[10:11]
	s_add_u32 s30, s27, s18
	v_add_co_u32_e64 v66, s[0:1], s23, v2
	s_addc_u32 s31, s28, s19
	s_nop 0
	v_addc_co_u32_e64 v67, s[0:1], -1, v3, s[0:1]
	v_add_co_u32_e32 v64, vcc, 0xffffd000, v2
	s_add_u32 s0, s14, s18
	s_nop 0
	v_addc_co_u32_e32 v65, vcc, -1, v3, vcc
	s_addc_u32 s1, s17, s19
	global_load_dword v104, v[2:3], off offset:-4096
	global_load_dwordx4 v[60:63], v1, s[30:31]
	global_load_dword v100, v[64:65], off
	global_load_dword v105, v[66:67], off
	s_nop 0
	global_load_dwordx4 v[64:67], v1, s[0:1]
	global_load_dwordx4 v[68:71], v1, s[0:1] offset:256
	global_load_dwordx4 v[72:75], v1, s[0:1] offset:512
	global_load_dwordx4 v[76:79], v1, s[0:1] offset:768
	global_load_dwordx4 v[80:83], v1, s[0:1] offset:1024
	global_load_dwordx4 v[84:87], v1, s[0:1] offset:1280
	global_load_dwordx4 v[88:91], v1, s[0:1] offset:1536
	global_load_dwordx4 v[92:95], v1, s[0:1] offset:1792
	global_load_dword v106, v[2:3], off
	s_add_u32 s18, s18, 16
	s_addc_u32 s19, s19, 0
	v_lshl_add_u64 v[2:3], v[2:3], 0, s[10:11]
	s_cmpk_eq_i32 s18, 0x100
	s_waitcnt vmcnt(20)
	v_mov_b32_e32 v52, v20
	s_waitcnt vmcnt(19)
	v_mov_b32_e32 v51, v24
	s_waitcnt vmcnt(18)
	v_mov_b32_e32 v53, v28
	s_waitcnt vmcnt(17)
	v_mov_b32_e32 v54, v32
	s_waitcnt vmcnt(16)
	v_mov_b32_e32 v56, v36
	v_mul_f32_e32 v0, v0, v12
	v_mul_f32_e32 v14, v48, v14
	s_waitcnt vmcnt(13)
	v_mul_f32_e32 v48, v50, v15
	v_mov_b32_e32 v50, v16
	v_mov_b32_e32 v55, v40
	v_mov_b32_e32 v57, v44
	v_mul_f32_e32 v12, v49, v13
	v_mov_b32_e32 v24, v17
	v_mov_b32_e32 v28, v21
	v_mov_b32_e32 v40, v33
	v_mov_b32_e32 v44, v37
	v_pk_fma_f32 v[4:5], v[0:1], v[50:51], v[4:5] op_sel_hi:[0,1,1]
	v_pk_fma_f32 v[8:9], v[0:1], v[52:53], v[8:9] op_sel_hi:[0,1,1]
	v_pk_fma_f32 v[6:7], v[0:1], v[54:55], v[6:7] op_sel_hi:[0,1,1]
	v_pk_fma_f32 v[10:11], v[0:1], v[56:57], v[10:11] op_sel_hi:[0,1,1]
	v_mov_b32_e32 v16, v18
	v_mov_b32_e32 v17, v26
	v_mov_b32_e32 v20, v22
	v_mov_b32_e32 v21, v30
	v_mov_b32_e32 v32, v34
	v_mov_b32_e32 v33, v42
	v_mov_b32_e32 v36, v38
	v_mov_b32_e32 v37, v46
	v_pk_fma_f32 v[4:5], v[12:13], v[24:25], v[4:5] op_sel_hi:[0,1,1]
	v_pk_fma_f32 v[8:9], v[12:13], v[28:29], v[8:9] op_sel_hi:[0,1,1]
	v_pk_fma_f32 v[6:7], v[12:13], v[40:41], v[6:7] op_sel_hi:[0,1,1]
	v_pk_fma_f32 v[10:11], v[12:13], v[44:45], v[10:11] op_sel_hi:[0,1,1]
	v_mov_b32_e32 v26, v19
	v_mov_b32_e32 v30, v23
	v_mov_b32_e32 v42, v35
	v_mov_b32_e32 v46, v39
	v_pk_fma_f32 v[4:5], v[14:15], v[16:17], v[4:5] op_sel_hi:[0,1,1]
	v_pk_fma_f32 v[8:9], v[14:15], v[20:21], v[8:9] op_sel_hi:[0,1,1]
	v_pk_fma_f32 v[6:7], v[14:15], v[32:33], v[6:7] op_sel_hi:[0,1,1]
	v_pk_fma_f32 v[10:11], v[14:15], v[36:37], v[10:11] op_sel_hi:[0,1,1]
	v_pk_fma_f32 v[4:5], v[48:49], v[26:27], v[4:5] op_sel_hi:[0,1,1]
	v_pk_fma_f32 v[8:9], v[48:49], v[30:31], v[8:9] op_sel_hi:[0,1,1]
	v_pk_fma_f32 v[6:7], v[48:49], v[42:43], v[6:7] op_sel_hi:[0,1,1]
	v_pk_fma_f32 v[10:11], v[48:49], v[46:47], v[10:11] op_sel_hi:[0,1,1]
	s_waitcnt vmcnt(7)
	v_mov_b32_e32 v108, v68
	s_waitcnt vmcnt(6)
	v_mov_b32_e32 v107, v72
	s_waitcnt vmcnt(5)
	v_mov_b32_e32 v109, v76
	s_waitcnt vmcnt(4)
	v_mov_b32_e32 v110, v80
	s_waitcnt vmcnt(3)
	v_mov_b32_e32 v112, v84
	v_mul_f32_e32 v100, v100, v60
	v_mul_f32_e32 v62, v104, v62
	s_waitcnt vmcnt(0)
	v_mul_f32_e32 v104, v106, v63
	v_mov_b32_e32 v106, v64
	v_mov_b32_e32 v111, v88
	v_mov_b32_e32 v113, v92
	v_mul_f32_e32 v60, v105, v61
	v_mov_b32_e32 v72, v65
	v_mov_b32_e32 v76, v69
	v_mov_b32_e32 v88, v81
	v_mov_b32_e32 v92, v85
	v_pk_fma_f32 v[4:5], v[100:101], v[106:107], v[4:5] op_sel_hi:[0,1,1]
	v_pk_fma_f32 v[8:9], v[100:101], v[108:109], v[8:9] op_sel_hi:[0,1,1]
	v_pk_fma_f32 v[6:7], v[100:101], v[110:111], v[6:7] op_sel_hi:[0,1,1]
	v_pk_fma_f32 v[10:11], v[100:101], v[112:113], v[10:11] op_sel_hi:[0,1,1]
	v_mov_b32_e32 v64, v66
	v_mov_b32_e32 v65, v74
	v_mov_b32_e32 v68, v70
	v_mov_b32_e32 v69, v78
	v_mov_b32_e32 v80, v82
	v_mov_b32_e32 v81, v90
	v_mov_b32_e32 v84, v86
	v_mov_b32_e32 v85, v94
	v_pk_fma_f32 v[4:5], v[60:61], v[72:73], v[4:5] op_sel_hi:[0,1,1]
	v_pk_fma_f32 v[8:9], v[60:61], v[76:77], v[8:9] op_sel_hi:[0,1,1]
	v_pk_fma_f32 v[6:7], v[60:61], v[88:89], v[6:7] op_sel_hi:[0,1,1]
	v_pk_fma_f32 v[10:11], v[60:61], v[92:93], v[10:11] op_sel_hi:[0,1,1]
	v_mov_b32_e32 v74, v67
	v_mov_b32_e32 v78, v71
	v_mov_b32_e32 v90, v83
	v_mov_b32_e32 v94, v87
	v_pk_fma_f32 v[4:5], v[62:63], v[64:65], v[4:5] op_sel_hi:[0,1,1]
	v_pk_fma_f32 v[8:9], v[62:63], v[68:69], v[8:9] op_sel_hi:[0,1,1]
	v_pk_fma_f32 v[6:7], v[62:63], v[80:81], v[6:7] op_sel_hi:[0,1,1]
	v_pk_fma_f32 v[10:11], v[62:63], v[84:85], v[10:11] op_sel_hi:[0,1,1]
	v_pk_fma_f32 v[4:5], v[104:105], v[74:75], v[4:5] op_sel_hi:[0,1,1]
	v_pk_fma_f32 v[8:9], v[104:105], v[78:79], v[8:9] op_sel_hi:[0,1,1]
	v_pk_fma_f32 v[6:7], v[104:105], v[90:91], v[6:7] op_sel_hi:[0,1,1]
	v_pk_fma_f32 v[10:11], v[104:105], v[94:95], v[10:11] op_sel_hi:[0,1,1]
	s_cbranch_scc0 .LBB0_87
; __device__ __forceinline__ unsigned pk2(float lo, float hi) { return f2bf(lo) | (f2bf(hi) << 16); }
; __device__ __forceinline__ void prologue(const Args& a, LAS unsigned char* lds, int vcu, int G) {
;     ...
;     for (int it = gw; it < DEPTH * 4 * 8 * 16; it += NGW) {
;         const int l = it >> 9, g = (it >> 7) & 3, c8 = (it >> 4) & 7, n = (it & 15) * 64 + lane;
;         const float* wo = a.wout + (size_t)l * DM * DM + (size_t)(g * 64) * DM + n;
;         const float* sc = a.ps + (size_t)l * PWD + g * 64;
;         const float* pr = a.pw + (((size_t)l * 4 + g) * 64 + c8 * 8) * 64;
;         float acc[8] = {0.f, 0.f, 0.f, 0.f, 0.f, 0.f, 0.f, 0.f};
; #pragma unroll 4
;         for (int dd = 0; dd < 64; ++dd) { const float wv = wo[(size_t)dd * DM] * sc[dd];
; #pragma unroll
;             for (int e = 0; e < 8; ++e) acc[e] += pr[e * 64 + dd] * wv; }
;         u32x4 o; o.x = pk2(acc[0], acc[1]); o.y = pk2(acc[2], acc[3]); o.z = pk2(acc[4], acc[5]); o.w = pk2(acc[6], acc[7]);
;         *(u32x4*)((bf16_t*)(ws + WS_W + (size_t)l * LW_SIZE + LW_OUT) + (size_t)n * DM + g * 64 + c8 * 8) = o;
;     }
	s_lshl_b32 s0, s26, 6
	s_and_b32 s0, s0, 0x3c0
	v_or_b32_e32 v0, s0, v135
	v_bfe_u32 v2, v11, 16, 1
	v_bfe_u32 v3, v10, 16, 1
	v_bfe_u32 v12, v9, 16, 1
	v_bfe_u32 v13, v8, 16, 1
	s_mul_i32 s0, s16, 0x2800000
	v_add3_u32 v8, v8, v13, s24
	v_add3_u32 v9, v9, v12, s24
	v_add3_u32 v3, v10, v3, s24
	v_add3_u32 v2, v11, v2, s24
	v_bfe_u32 v10, v4, 16, 1
	v_bfe_u32 v11, v5, 16, 1
	v_bfe_u32 v12, v6, 16, 1
	v_bfe_u32 v13, v7, 16, 1
	s_mul_hi_i32 s1, s16, 0x2800000
	s_add_u32 s0, s8, s0
	v_add3_u32 v7, v7, v13, s24
	v_add3_u32 v6, v6, v12, s24
	v_add3_u32 v5, v5, v11, s24
	v_add3_u32 v4, v4, v10, s24
	s_addc_u32 s1, s9, s1
	v_lshlrev_b32_e32 v0, 11, v0
	v_lshrrev_b32_e32 v10, 16, v4
	v_lshrrev_b32_e32 v11, 16, v5
	v_lshrrev_b32_e32 v4, 16, v6
	v_lshrrev_b32_e32 v5, 16, v7
	v_lshl_add_u64 v[6:7], s[0:1], 0, v[0:1]
	s_and_b32 s14, s26, 0x180
	v_lshl_add_u64 v[6:7], v[6:7], 0, s[14:15]
	s_and_b32 s14, s26, 0x70
	v_lshl_add_u64 v[6:7], v[6:7], 0, s[14:15]
	v_add_co_u32_e32 v6, vcc, 0x1580000, v6
	s_add_i32 s26, s26, s3
	s_add_i32 s22, s22, s13
	v_and_or_b32 v5, v2, s25, v5
	v_and_or_b32 v4, v3, s25, v4
	v_and_or_b32 v3, v9, s25, v11
	v_and_or_b32 v2, v8, s25, v10
	v_addc_co_u32_e32 v7, vcc, 0, v7, vcc
	s_cmpk_gt_i32 s26, 0x7ff
	global_store_dwordx4 v[6:7], v[2:5], off
	s_cbranch_scc0 .LBB0_86
